# conv walker: row compute starts after the 4 row loads (vmcnt(6)); the dt operand loads are waited for and their 4 MFMAs issued after the second row, overlapping their latency with the row math
# baseline (speedup 1.0000x reference)
; __device__ __forceinline__ void phase_ssd_conv_dt(const Args& a, int j) {
;     ...
;     for (int t = 0; t < 64; ++t) {
;         float cur[8], o[8];
;         unpack8(*(const uint4*)(p + (size_t)t * BIGW), cur);
;         if (has_dt && !(t & 1)) {
;             const int k0 = (t >> 1) * 32;
;             const bf16x8 xf = *(const bf16x8*)(xp + k0), wf0 = *(const bf16x8*)(w0p + k0), wf1 = *(const bf16x8*)(w1p + k0);
;             d0 = __builtin_amdgcn_mfma_f32_16x16x32_bf16(wf0, xf, d0, 0, 0, 0);
;             d1 = __builtin_amdgcn_mfma_f32_16x16x32_bf16(wf1, xf, d1, 0, 0, 0);
;         }
.LBB0_799:
	v_lshl_add_u64 v[4:5], s[30:31], 0, v[86:87]
	v_add_co_u32_e32 v58, vcc, 0x9301000, v4
	v_cndmask_b32_e64 v1, 0, 1, s[4:5]
	s_nop 0
	v_addc_co_u32_e32 v59, vcc, 0, v5, vcc
	global_load_dwordx4 v[112:115], v[58:59], off
	v_add_co_u32_e32 v58, vcc, s1, v4
	s_nop 1
	v_addc_co_u32_e32 v59, vcc, 0, v5, vcc
	global_load_dwordx4 v[116:119], v[58:59], off
	v_add_co_u32_e32 v58, vcc, 0x9307000, v4
	s_nop 1
	v_addc_co_u32_e32 v59, vcc, 0, v5, vcc
	global_load_dwordx4 v[120:123], v[58:59], off
	v_add_co_u32_e32 v58, vcc, s8, v4
	s_nop 1
	v_addc_co_u32_e32 v59, vcc, 0, v5, vcc
	global_load_dwordx4 v[124:127], v[58:59], off
	v_cmp_ne_u32_e64 s[6:7], 1, v1
	s_andn2_b64 vcc, exec, s[4:5]
	v_lshl_add_u64 v[96:97], s[30:31], 0, v[92:93]
	v_lshl_add_u64 v[94:95], s[30:31], 0, v[90:91]
	s_cbranch_vccnz .LBB0_801
	v_add_co_u32_e32 v98, vcc, 0x7300000, v96
	s_nop 1
	v_addc_co_u32_e32 v99, vcc, 0, v97, vcc
	v_add_co_u32_e32 v102, vcc, 0xc00000, v94
	s_nop 1
	v_addc_co_u32_e32 v103, vcc, 0, v95, vcc
	global_load_dwordx4 v[128:131], v[102:103], off
	global_load_dwordx4 v[132:135], v[98:99], off
	global_load_dwordx4 v[140:143], v[102:103], off offset:64
	global_load_dwordx4 v[144:147], v[98:99], off offset:64
	v_add_co_u32_e32 v98, vcc, 0xc08000, v94
	s_nop 1
	v_addc_co_u32_e32 v99, vcc, 0, v95, vcc
	global_load_dwordx4 v[136:139], v[98:99], off
	global_load_dwordx4 v[148:151], v[98:99], off offset:64
	s_waitcnt vmcnt(6)
	s_branch .Lcw_rows

; __device__ __forceinline__ uint4 pack8(const float* f) { uint4 o; o.x = pk2(f[0], f[1]); o.y = pk2(f[2], f[3]); o.z = pk2(f[4], f[5]); o.w = pk2(f[6], f[7]); return o; }
; __device__ __forceinline__ float silu_f(float x) { return x * __builtin_amdgcn_rcpf(1.0f + __expf(-x)); }
; __device__ __forceinline__ void phase_ssd_conv_dt(const Args& a, int j) {
;     ...
;     for (int t = 0; t < 64; ++t) {
;         float cur[8], o[8];
;         unpack8(*(const uint4*)(p + (size_t)t * BIGW), cur);
;         if (has_dt && !(t & 1)) {
;             const int k0 = (t >> 1) * 32;
;             const bf16x8 xf = *(const bf16x8*)(xp + k0), wf0 = *(const bf16x8*)(w0p + k0), wf1 = *(const bf16x8*)(w1p + k0);
;             d0 = __builtin_amdgcn_mfma_f32_16x16x32_bf16(wf0, xf, d0, 0, 0, 0);
;             d1 = __builtin_amdgcn_mfma_f32_16x16x32_bf16(wf1, xf, d1, 0, 0, 0);
;         }
; #pragma unroll
;         for (int e = 0; e < 8; ++e) { const float v = bb[e] + wt[0][e] * h0[e] + wt[1][e] * h1[e] + wt[2][e] * h2[e] + wt[3][e] * cur[e]; o[e] = silu_f(v); h0[e] = h1[e]; h1[e] = h2[e]; h2[e] = cur[e]; }
;         *(uint4*)(p + (size_t)t * BIGW) = pack8(o);
.Lcw_rows:
	v_lshlrev_b32_e32 v106, 16, v112
	v_and_b32_e32 v105, 0xffff0000, v112
	v_fma_f32 v58, v22, v75, v54
	v_fmac_f32_e32 v58, v26, v85
	v_fmac_f32_e32 v58, v34, v89
	v_fmac_f32_e32 v58, v42, v106
	v_lshlrev_b32_e32 v104, 16, v113
	v_and_b32_e32 v103, 0xffff0000, v113
	v_mul_f32_e32 v59, 0xbfb8aa3b, v58
	v_exp_f32_e32 v59, v59
	v_lshlrev_b32_e32 v102, 16, v114
	v_and_b32_e32 v101, 0xffff0000, v114
	v_lshlrev_b32_e32 v2, 16, v115
	v_add_f32_e32 v59, 1.0, v59
	v_rcp_f32_e32 v59, v59
	v_and_b32_e32 v1, 0xffff0000, v115
	v_fma_f32 v67, v18, v67, v50
	v_fmac_f32_e32 v67, v30, v73
	v_mul_f32_e32 v58, v58, v59
	v_fma_f32 v59, v23, v74, v55
	v_fmac_f32_e32 v59, v27, v84
	v_fmac_f32_e32 v59, v35, v88
	v_fmac_f32_e32 v59, v43, v105
	v_mul_f32_e32 v60, 0xbfb8aa3b, v59
	v_exp_f32_e32 v60, v60
	v_fmac_f32_e32 v67, v38, v81
	v_fmac_f32_e32 v67, v46, v102
	v_fma_f32 v66, v19, v66, v51
	v_add_f32_e32 v60, 1.0, v60
	v_rcp_f32_e32 v60, v60
	v_fmac_f32_e32 v66, v31, v72
	v_fmac_f32_e32 v66, v39, v80
	v_fmac_f32_e32 v66, v47, v101
	v_mul_f32_e32 v59, v59, v60
	v_fma_f32 v60, v24, v71, v56
	v_fmac_f32_e32 v60, v28, v77
	v_fmac_f32_e32 v60, v36, v83
	v_fmac_f32_e32 v60, v44, v104
	v_mul_f32_e32 v61, 0xbfb8aa3b, v60
	v_exp_f32_e32 v61, v61
	v_fma_f32 v65, v20, v65, v52
	v_fmac_f32_e32 v65, v32, v69
	v_fmac_f32_e32 v65, v40, v79
	v_add_f32_e32 v61, 1.0, v61
	v_rcp_f32_e32 v61, v61
	v_fmac_f32_e32 v65, v48, v2
	v_fma_f32 v64, v21, v64, v53
	v_fmac_f32_e32 v64, v33, v68
	v_mul_f32_e32 v60, v60, v61
	v_fma_f32 v61, v25, v70, v57
	v_fmac_f32_e32 v61, v29, v76
	v_fmac_f32_e32 v61, v37, v82
	v_fmac_f32_e32 v61, v45, v103
	v_mul_f32_e32 v70, 0xbfb8aa3b, v61
	v_exp_f32_e32 v70, v70
	v_fmac_f32_e32 v64, v41, v78
	v_fmac_f32_e32 v64, v49, v1
	s_mov_b64 s[2:3], 0x9301000
	v_add_f32_e32 v70, 1.0, v70
	v_rcp_f32_e32 v70, v70
	v_lshl_add_u64 v[98:99], v[4:5], 0, s[2:3]
	v_cvt_pk_bf16_f32 v58, v58, v59
	v_fma_f32 v77, v24, v77, v56
	v_mul_f32_e32 v61, v61, v70
	v_mul_f32_e32 v70, 0xbfb8aa3b, v67
	v_exp_f32_e32 v70, v70
	v_cvt_pk_bf16_f32 v59, v60, v61
	v_fmac_f32_e32 v77, v28, v83
	v_fmac_f32_e32 v77, v36, v104
	v_add_f32_e32 v70, 1.0, v70
	v_rcp_f32_e32 v70, v70
	v_fma_f32 v76, v25, v76, v57
	v_fmac_f32_e32 v76, v29, v82
	v_fmac_f32_e32 v76, v37, v103
	v_mul_f32_e32 v67, v67, v70
	v_mul_f32_e32 v70, 0xbfb8aa3b, v66
	v_exp_f32_e32 v70, v70
	v_fma_f32 v73, v18, v73, v50
	v_fmac_f32_e32 v73, v30, v81
	v_fmac_f32_e32 v73, v38, v102
	v_add_f32_e32 v70, 1.0, v70
	v_rcp_f32_e32 v70, v70
	v_fma_f32 v72, v19, v72, v51
	v_fmac_f32_e32 v72, v31, v80
	v_fmac_f32_e32 v72, v39, v101
	v_mul_f32_e32 v66, v66, v70
	v_mul_f32_e32 v70, 0xbfb8aa3b, v65
	v_exp_f32_e32 v70, v70
	v_cvt_pk_bf16_f32 v60, v67, v66
	v_fma_f32 v69, v20, v69, v52
	v_fmac_f32_e32 v69, v32, v79
	v_add_f32_e32 v70, 1.0, v70
	v_rcp_f32_e32 v70, v70
	v_fmac_f32_e32 v69, v40, v2
	v_fma_f32 v68, v21, v68, v53
	v_fmac_f32_e32 v68, v33, v78
	v_mul_f32_e32 v65, v65, v70
	v_mul_f32_e32 v70, 0xbfb8aa3b, v64
	v_exp_f32_e32 v70, v70
	v_fmac_f32_e32 v68, v41, v1
	v_add_f32_e32 v70, 1.0, v70
	v_rcp_f32_e32 v70, v70
	s_nop 0
	v_mul_f32_e32 v64, v64, v70
	v_cvt_pk_bf16_f32 v61, v65, v64
	global_store_dwordx4 v[98:99], v[58:61], off
	s_nop 1
	v_add_co_u32_e32 v58, vcc, s1, v4
	v_fma_f32 v60, v22, v85, v54
	s_nop 0
	v_addc_co_u32_e32 v59, vcc, 0, v5, vcc
	s_nop 0
	v_fmac_f32_e32 v60, v26, v89
	v_fmac_f32_e32 v60, v34, v106
	s_nop 0
	v_lshlrev_b32_e32 v75, 16, v116
	v_fmac_f32_e32 v60, v42, v75
	v_mul_f32_e32 v61, 0xbfb8aa3b, v60
	v_exp_f32_e32 v61, v61
	v_and_b32_e32 v74, 0xffff0000, v116
	v_lshlrev_b32_e32 v71, 16, v117
	v_fmac_f32_e32 v77, v44, v71
	v_add_f32_e32 v61, 1.0, v61
	v_rcp_f32_e32 v61, v61
	v_and_b32_e32 v70, 0xffff0000, v117
	v_fmac_f32_e32 v76, v45, v70
	v_lshlrev_b32_e32 v67, 16, v118
	v_mul_f32_e32 v60, v60, v61
	v_fma_f32 v61, v23, v84, v55
	v_fmac_f32_e32 v61, v27, v88
	v_fmac_f32_e32 v61, v35, v105
	v_fmac_f32_e32 v61, v43, v74
	v_mul_f32_e32 v84, 0xbfb8aa3b, v61
	v_exp_f32_e32 v84, v84
	v_fmac_f32_e32 v73, v46, v67
	v_and_b32_e32 v66, 0xffff0000, v118
	v_fmac_f32_e32 v72, v47, v66
	v_add_f32_e32 v84, 1.0, v84
	v_rcp_f32_e32 v84, v84
	v_lshlrev_b32_e32 v65, 16, v119
	v_fmac_f32_e32 v69, v48, v65
	v_and_b32_e32 v64, 0xffff0000, v119
	v_mul_f32_e32 v61, v61, v84
	v_mul_f32_e32 v84, 0xbfb8aa3b, v77
	v_exp_f32_e32 v84, v84
	v_fmac_f32_e32 v68, v49, v64
	v_cvt_pk_bf16_f32 v108, v60, v61
	v_add_f32_e32 v84, 1.0, v84
	v_rcp_f32_e32 v84, v84
	s_nop 0
	v_mul_f32_e32 v77, v77, v84
	v_mul_f32_e32 v84, 0xbfb8aa3b, v76
	v_exp_f32_e32 v84, v84
	s_nop 0
	v_add_f32_e32 v84, 1.0, v84
	v_rcp_f32_e32 v84, v84
	s_nop 0
	v_mul_f32_e32 v76, v76, v84
	v_mul_f32_e32 v84, 0xbfb8aa3b, v73
	v_exp_f32_e32 v84, v84
	v_cvt_pk_bf16_f32 v109, v77, v76
	s_nop 0
	v_add_f32_e32 v84, 1.0, v84
	v_rcp_f32_e32 v84, v84
	s_nop 0
	v_mul_f32_e32 v73, v73, v84
	v_mul_f32_e32 v84, 0xbfb8aa3b, v72
	v_exp_f32_e32 v84, v84
	s_nop 0
	v_add_f32_e32 v84, 1.0, v84
	v_rcp_f32_e32 v84, v84
	s_nop 0
	v_mul_f32_e32 v72, v72, v84
	v_mul_f32_e32 v84, 0xbfb8aa3b, v69
	v_exp_f32_e32 v84, v84
	v_cvt_pk_bf16_f32 v110, v73, v72
	s_nop 0
	v_add_f32_e32 v84, 1.0, v84
	v_rcp_f32_e32 v84, v84
	s_nop 0
	v_mul_f32_e32 v69, v69, v84
	v_mul_f32_e32 v84, 0xbfb8aa3b, v68
	v_exp_f32_e32 v84, v84
	s_nop 0
	v_add_f32_e32 v84, 1.0, v84
	v_rcp_f32_e32 v84, v84
	s_nop 0
	v_mul_f32_e32 v68, v68, v84
	v_cvt_pk_bf16_f32 v111, v69, v68
	global_store_dwordx4 v[58:59], v[108:111], off
	s_and_b64 vcc, exec, s[6:7]
	s_cbranch_vccnz .LBB0_798
	s_waitcnt vmcnt(2)
	v_mfma_f32_16x16x32_bf16 v[14:17], v[128:131], v[132:135], v[14:17]
	v_mfma_f32_16x16x32_bf16 v[10:13], v[136:139], v[132:135], v[10:13]
	v_mfma_f32_16x16x32_bf16 v[14:17], v[140:143], v[144:147], v[14:17]
	v_mfma_f32_16x16x32_bf16 v[10:13], v[148:151], v[144:147], v[10:13]
	s_branch .LBB0_798
